# scan loader: w/kk/ka operand arrays by LDS-DMA (global_load_lds_dwordx4) into a 5-slot LDS ring read directly by the compute waves, 12 ds_write_b128 per chunk removed
# speedup vs baseline: 1.0168x; 1.0132x over previous
.LBB0_1047:
	s_and_b64 vcc, exec, s[24:25]
	s_cbranch_vccz .LBB0_1279
	s_waitcnt vmcnt(0)
	v_mov_b32_e32 v4, v232
	s_nop 0
	v_ashrrev_i32_e32 v0, 6, v4
	v_and_b32_e32 v54, 15, v4
	v_cmp_gt_i32_e32 vcc, 4, v0
	v_lshlrev_b32_e32 v38, 2, v54
	s_barrier
	s_and_saveexec_b64 s[24:25], vcc
	s_xor_b64 s[24:25], exec, s[24:25]
	s_cbranch_execz .LBB0_1051
	v_lshlrev_b32_e32 v2, 2, v4
	s_waitcnt lgkmcnt(0)
	s_barrier
	v_and_b32_e32 v2, 0xc0, v2
	v_lshl_or_b32 v85, v0, 8, v2
	v_mov_b32_e32 v74, 0
	v_lshlrev_b32_e32 v83, 4, v54
	v_add3_u32 v87, 0, v85, v38
	s_mov_b32 s26, 0
	s_mov_b32 s96, 0x12800
	v_mov_b32_e32 v75, v74
	v_mov_b32_e32 v76, v74
	v_mov_b32_e32 v77, v74
	s_setprio 3
.LBB0_1050:
	s_and_b32 s2, s26, 1
	s_mul_i32 s3, s2, 0x5400
	v_lshl_add_u32 v88, s2, 14, v87
	s_add_i32 s2, s3, 0
	v_add_u32_e32 v0, s2, v85
	v_add_u32_e32 v89, s2, v83
	v_add_u32_e32 v90, s96, v83
	s_add_i32 s96, s96, 0x3000
	s_cmp_eq_u32 s96, 0x1e800
	s_cselect_b32 s96, 0x20200, s96
	s_cmp_eq_u32 s96, 0x23200
	s_cselect_b32 s96, 0x12800, s96
	ds_read_b128 v[14:17], v0 offset:20480
	ds_read_b128 v[10:13], v0 offset:20496
	ds_read_b128 v[6:9], v0 offset:20512
	ds_read_b128 v[2:5], v0 offset:20528
	ds_read_b128 v[62:65], v90
	ds_read_b128 v[46:49], v90 offset:256
	ds_read_b128 v[66:69], v90 offset:4096
	ds_read_b128 v[50:53], v90 offset:4352
	ds_read_b128 v[54:57], v89 offset:16384
	ds_read_b128 v[26:29], v89 offset:16640
	ds_read_b128 v[78:81], v89 offset:4096
	ds_read_b128 v[34:37], v90 offset:512
	ds_read_b128 v[58:61], v89 offset:4352
	ds_read_b128 v[30:33], v89 offset:4608
	ds_read_b128 v[70:73], v90 offset:8192
	ds_read_b128 v[38:41], v90 offset:4608
	ds_read_b128 v[42:45], v90 offset:8448
	ds_read_b128 v[22:25], v90 offset:8704
	ds_read_b128 v[18:21], v89 offset:16896
	s_waitcnt lgkmcnt(12)
	v_pk_mul_f32 v[66:67], v[74:75], v[66:67]
	s_waitcnt lgkmcnt(8)
	v_pk_mul_f32 v[78:79], v[14:15], v[78:79] op_sel_hi:[0,1]
	v_pk_fma_f32 v[66:67], v[76:77], v[68:69], v[66:67]
	v_pk_mul_f32 v[80:81], v[14:15], v[80:81] op_sel_hi:[0,1]
	v_add_f32_e32 v66, v66, v67
	v_pk_fma_f32 v[62:63], v[74:75], v[62:63], v[78:79]
	v_pk_fma_f32 v[64:65], v[76:77], v[64:65], v[80:81]
	v_add_f32_dpp v66, v66, v66 quad_perm:[1,0,3,2] row_mask:0xf bank_mask:0xf bound_ctrl:1
	v_mov_b32_e32 v0, v17
	v_mov_b32_e32 v82, v13
	v_add_f32_dpp v66, v66, v66 quad_perm:[2,3,0,1] row_mask:0xf bank_mask:0xf bound_ctrl:1
	v_mov_b32_e32 v84, v9
	v_mov_b32_e32 v86, v5
	v_add_f32_dpp v66, v66, v66 row_half_mirror row_mask:0xf bank_mask:0xf bound_ctrl:1
	s_add_i32 s26, s26, 1
	s_cmpk_eq_i32 s26, 0x110
	v_add_f32_dpp v66, v66, v66 row_ror:8 row_mask:0xf bank_mask:0xf bound_ctrl:1
	s_waitcnt lgkmcnt(4)
	v_pk_fma_f32 v[62:63], v[70:71], v[66:67], v[62:63] op_sel_hi:[1,0,1] neg_lo:[1,0,0] neg_hi:[1,0,0]
	v_pk_fma_f32 v[64:65], v[72:73], v[66:67], v[64:65] op_sel_hi:[1,0,1] neg_lo:[1,0,0] neg_hi:[1,0,0]
	v_pk_mul_f32 v[50:51], v[50:51], v[62:63]
	v_pk_mul_f32 v[46:47], v[46:47], v[62:63]
	v_pk_fma_f32 v[50:51], v[52:53], v[64:65], v[50:51]
	v_pk_fma_f32 v[66:67], v[14:15], v[58:59], v[46:47] op_sel:[1,0,0]
	v_add_f32_e32 v47, v50, v51
	v_pk_mul_f32 v[48:49], v[48:49], v[64:65]
	v_pk_mul_f32 v[56:57], v[56:57], v[64:65]
	v_add_f32_dpp v68, v47, v47 quad_perm:[1,0,3,2] row_mask:0xf bank_mask:0xf bound_ctrl:1
	v_pk_fma_f32 v[14:15], v[14:15], v[60:61], v[48:49] op_sel:[1,0,0]
	v_pk_fma_f32 v[54:55], v[54:55], v[62:63], v[56:57]
	v_add_f32_dpp v68, v68, v68 quad_perm:[2,3,0,1] row_mask:0xf bank_mask:0xf bound_ctrl:1
	v_add_f32_e32 v46, v54, v55
	ds_write_b32 v88, v46 offset:43008
	v_add_f32_dpp v68, v68, v68 row_half_mirror row_mask:0xf bank_mask:0xf bound_ctrl:1
	ds_read_b128 v[46:49], v90 offset:768
	ds_read_b128 v[50:53], v89 offset:4864
	ds_read_b128 v[54:57], v90 offset:4864
	ds_read_b128 v[58:61], v90 offset:8960
	ds_read_b128 v[62:65], v89 offset:17152
	v_add_f32_dpp v68, v68, v68 row_ror:8 row_mask:0xf bank_mask:0xf bound_ctrl:1
	s_waitcnt lgkmcnt(8)
	v_pk_fma_f32 v[42:43], v[42:43], v[68:69], v[66:67] op_sel_hi:[1,0,1] neg_lo:[1,0,0] neg_hi:[1,0,0]
	v_pk_fma_f32 v[14:15], v[44:45], v[68:69], v[14:15] op_sel_hi:[1,0,1] neg_lo:[1,0,0] neg_hi:[1,0,0]
	v_pk_mul_f32 v[38:39], v[38:39], v[42:43]
	v_pk_mul_f32 v[28:29], v[28:29], v[14:15]
	v_pk_mul_f32 v[36:37], v[36:37], v[14:15]
	v_pk_fma_f32 v[14:15], v[40:41], v[14:15], v[38:39]
	v_pk_mul_f32 v[34:35], v[34:35], v[42:43]
	v_add_f32_e32 v14, v14, v15
	v_pk_fma_f32 v[26:27], v[26:27], v[42:43], v[28:29]
	v_pk_fma_f32 v[42:43], v[16:17], v[30:31], v[34:35] op_sel_hi:[0,1,1]
	v_add_f32_dpp v66, v14, v14 quad_perm:[1,0,3,2] row_mask:0xf bank_mask:0xf bound_ctrl:1
	v_pk_fma_f32 v[44:45], v[16:17], v[32:33], v[36:37] op_sel_hi:[0,1,1]
	v_add_f32_e32 v16, v26, v27
	v_add_f32_dpp v66, v66, v66 quad_perm:[2,3,0,1] row_mask:0xf bank_mask:0xf bound_ctrl:1
	ds_write_b32 v88, v16 offset:44032
	ds_read_b128 v[14:17], v90 offset:1024
	ds_read_b128 v[26:29], v89 offset:5120
	ds_read_b128 v[30:33], v90 offset:5120
	ds_read_b128 v[34:37], v90 offset:9216
	ds_read_b128 v[38:41], v89 offset:17408
	v_add_f32_dpp v66, v66, v66 row_half_mirror row_mask:0xf bank_mask:0xf bound_ctrl:1
	s_nop 1
	v_add_f32_dpp v66, v66, v66 row_ror:8 row_mask:0xf bank_mask:0xf bound_ctrl:1
	s_waitcnt lgkmcnt(8)
	v_pk_fma_f32 v[22:23], v[22:23], v[66:67], v[42:43] op_sel_hi:[1,0,1] neg_lo:[1,0,0] neg_hi:[1,0,0]
	v_pk_fma_f32 v[24:25], v[24:25], v[66:67], v[44:45] op_sel_hi:[1,0,1] neg_lo:[1,0,0] neg_hi:[1,0,0]
	v_pk_mul_f32 v[42:43], v[54:55], v[22:23]
	v_pk_mul_f32 v[20:21], v[20:21], v[24:25]
	v_pk_mul_f32 v[44:45], v[46:47], v[22:23]
	v_pk_mul_f32 v[46:47], v[48:49], v[24:25]
	v_pk_fma_f32 v[18:19], v[18:19], v[22:23], v[20:21]
	v_pk_fma_f32 v[20:21], v[56:57], v[24:25], v[42:43]
	v_pk_fma_f32 v[54:55], v[0:1], v[50:51], v[44:45] op_sel_hi:[0,1,1]
	v_pk_fma_f32 v[56:57], v[0:1], v[52:53], v[46:47] op_sel_hi:[0,1,1]
	v_add_f32_e32 v0, v18, v19
	v_add_f32_e32 v18, v20, v21
	ds_write_b32 v88, v0 offset:45056
	s_nop 0
	v_add_f32_dpp v0, v18, v18 quad_perm:[1,0,3,2] row_mask:0xf bank_mask:0xf bound_ctrl:1
	ds_read_b128 v[18:21], v90 offset:1280
	ds_read_b128 v[22:25], v89 offset:5376
	v_add_f32_dpp v0, v0, v0 quad_perm:[2,3,0,1] row_mask:0xf bank_mask:0xf bound_ctrl:1
	ds_read_b128 v[42:45], v90 offset:5376
	ds_read_b128 v[46:49], v90 offset:9472
	v_add_f32_dpp v0, v0, v0 row_half_mirror row_mask:0xf bank_mask:0xf bound_ctrl:1
	ds_read_b128 v[50:53], v89 offset:17664
	s_nop 0
	v_add_f32_dpp v0, v0, v0 row_ror:8 row_mask:0xf bank_mask:0xf bound_ctrl:1
	s_waitcnt lgkmcnt(8)
	v_pk_fma_f32 v[54:55], v[58:59], v[0:1], v[54:55] op_sel_hi:[1,0,1] neg_lo:[1,0,0] neg_hi:[1,0,0]
	v_pk_fma_f32 v[56:57], v[60:61], v[0:1], v[56:57] op_sel_hi:[1,0,1] neg_lo:[1,0,0] neg_hi:[1,0,0]
	v_pk_mul_f32 v[30:31], v[30:31], v[54:55]
	v_pk_mul_f32 v[58:59], v[64:65], v[56:57]
	v_pk_mul_f32 v[14:15], v[14:15], v[54:55]
	v_pk_fma_f32 v[54:55], v[62:63], v[54:55], v[58:59]
	v_pk_fma_f32 v[30:31], v[32:33], v[56:57], v[30:31]
	v_pk_fma_f32 v[62:63], v[10:11], v[26:27], v[14:15] op_sel_hi:[0,1,1]
	v_add_f32_e32 v0, v54, v55
	v_add_f32_e32 v14, v30, v31
	ds_write_b32 v88, v0 offset:46080
	v_pk_mul_f32 v[16:17], v[16:17], v[56:57]
	v_add_f32_dpp v0, v14, v14 quad_perm:[1,0,3,2] row_mask:0xf bank_mask:0xf bound_ctrl:1
	v_pk_fma_f32 v[64:65], v[10:11], v[28:29], v[16:17] op_sel_hi:[0,1,1]
	ds_read_b128 v[14:17], v90 offset:1536
	v_add_f32_dpp v0, v0, v0 quad_perm:[2,3,0,1] row_mask:0xf bank_mask:0xf bound_ctrl:1
	ds_read_b128 v[26:29], v89 offset:5632
	ds_read_b128 v[30:33], v90 offset:5632
	v_add_f32_dpp v0, v0, v0 row_half_mirror row_mask:0xf bank_mask:0xf bound_ctrl:1
	ds_read_b128 v[54:57], v90 offset:9728
	ds_read_b128 v[58:61], v89 offset:17920
	v_add_f32_dpp v0, v0, v0 row_ror:8 row_mask:0xf bank_mask:0xf bound_ctrl:1
	s_waitcnt lgkmcnt(8)
	v_pk_fma_f32 v[34:35], v[34:35], v[0:1], v[62:63] op_sel_hi:[1,0,1] neg_lo:[1,0,0] neg_hi:[1,0,0]
	v_pk_fma_f32 v[36:37], v[36:37], v[0:1], v[64:65] op_sel_hi:[1,0,1] neg_lo:[1,0,0] neg_hi:[1,0,0]
	v_pk_mul_f32 v[42:43], v[42:43], v[34:35]
	v_pk_mul_f32 v[40:41], v[40:41], v[36:37]
	v_pk_mul_f32 v[18:19], v[18:19], v[34:35]
	v_pk_mul_f32 v[20:21], v[20:21], v[36:37]
	v_pk_fma_f32 v[34:35], v[38:39], v[34:35], v[40:41]
	v_pk_fma_f32 v[36:37], v[44:45], v[36:37], v[42:43]
	v_pk_fma_f32 v[62:63], v[10:11], v[22:23], v[18:19] op_sel:[1,0,0]
	v_add_f32_e32 v0, v34, v35
	v_add_f32_e32 v18, v36, v37
	ds_write_b32 v88, v0 offset:47104
	v_pk_fma_f32 v[10:11], v[10:11], v[24:25], v[20:21] op_sel:[1,0,0]
	v_add_f32_dpp v0, v18, v18 quad_perm:[1,0,3,2] row_mask:0xf bank_mask:0xf bound_ctrl:1
	ds_read_b128 v[18:21], v90 offset:1792
	ds_read_b128 v[22:25], v89 offset:5888
	v_add_f32_dpp v0, v0, v0 quad_perm:[2,3,0,1] row_mask:0xf bank_mask:0xf bound_ctrl:1
	ds_read_b128 v[34:37], v90 offset:5888
	ds_read_b128 v[38:41], v90 offset:9984
	v_add_f32_dpp v0, v0, v0 row_half_mirror row_mask:0xf bank_mask:0xf bound_ctrl:1
	ds_read_b128 v[42:45], v89 offset:18176
	s_nop 0
	v_add_f32_dpp v0, v0, v0 row_ror:8 row_mask:0xf bank_mask:0xf bound_ctrl:1
	s_waitcnt lgkmcnt(8)
	v_pk_fma_f32 v[46:47], v[46:47], v[0:1], v[62:63] op_sel_hi:[1,0,1] neg_lo:[1,0,0] neg_hi:[1,0,0]
	v_pk_fma_f32 v[10:11], v[48:49], v[0:1], v[10:11] op_sel_hi:[1,0,1] neg_lo:[1,0,0] neg_hi:[1,0,0]
	v_pk_mul_f32 v[30:31], v[30:31], v[46:47]
	v_pk_mul_f32 v[48:49], v[52:53], v[10:11]
	v_pk_mul_f32 v[14:15], v[14:15], v[46:47]
	v_pk_mul_f32 v[16:17], v[16:17], v[10:11]
	v_pk_fma_f32 v[46:47], v[50:51], v[46:47], v[48:49]
	v_pk_fma_f32 v[10:11], v[32:33], v[10:11], v[30:31]
	v_add_f32_e32 v0, v46, v47
	v_add_f32_e32 v10, v10, v11
	ds_write_b32 v88, v0 offset:48128
	v_pk_fma_f32 v[50:51], v[12:13], v[26:27], v[14:15] op_sel_hi:[0,1,1]
	v_add_f32_dpp v0, v10, v10 quad_perm:[1,0,3,2] row_mask:0xf bank_mask:0xf bound_ctrl:1
	v_pk_fma_f32 v[52:53], v[12:13], v[28:29], v[16:17] op_sel_hi:[0,1,1]
	ds_read_b128 v[10:13], v90 offset:2048
	v_add_f32_dpp v0, v0, v0 quad_perm:[2,3,0,1] row_mask:0xf bank_mask:0xf bound_ctrl:1
	ds_read_b128 v[14:17], v89 offset:6144
	ds_read_b128 v[26:29], v90 offset:6144
	v_add_f32_dpp v0, v0, v0 row_half_mirror row_mask:0xf bank_mask:0xf bound_ctrl:1
	ds_read_b128 v[30:33], v90 offset:10240
	ds_read_b128 v[46:49], v89 offset:18432
	v_add_f32_dpp v0, v0, v0 row_ror:8 row_mask:0xf bank_mask:0xf bound_ctrl:1
	s_waitcnt lgkmcnt(8)
	v_pk_fma_f32 v[50:51], v[54:55], v[0:1], v[50:51] op_sel_hi:[1,0,1] neg_lo:[1,0,0] neg_hi:[1,0,0]
	v_pk_fma_f32 v[52:53], v[56:57], v[0:1], v[52:53] op_sel_hi:[1,0,1] neg_lo:[1,0,0] neg_hi:[1,0,0]
	v_pk_mul_f32 v[34:35], v[34:35], v[50:51]
	v_pk_mul_f32 v[54:55], v[60:61], v[52:53]
	v_pk_mul_f32 v[18:19], v[18:19], v[50:51]
	v_pk_fma_f32 v[50:51], v[58:59], v[50:51], v[54:55]
	v_pk_fma_f32 v[34:35], v[36:37], v[52:53], v[34:35]
	v_pk_fma_f32 v[58:59], v[82:83], v[22:23], v[18:19] op_sel_hi:[0,1,1]
	v_add_f32_e32 v0, v50, v51
	v_add_f32_e32 v18, v34, v35
	ds_write_b32 v88, v0 offset:49152
	v_pk_mul_f32 v[20:21], v[20:21], v[52:53]
	v_add_f32_dpp v0, v18, v18 quad_perm:[1,0,3,2] row_mask:0xf bank_mask:0xf bound_ctrl:1
	v_pk_fma_f32 v[60:61], v[82:83], v[24:25], v[20:21] op_sel_hi:[0,1,1]
	ds_read_b128 v[18:21], v90 offset:2304
	v_add_f32_dpp v0, v0, v0 quad_perm:[2,3,0,1] row_mask:0xf bank_mask:0xf bound_ctrl:1
	ds_read_b128 v[22:25], v89 offset:6400
	ds_read_b128 v[34:37], v90 offset:6400
	v_add_f32_dpp v0, v0, v0 row_half_mirror row_mask:0xf bank_mask:0xf bound_ctrl:1
	ds_read_b128 v[50:53], v90 offset:10496
	ds_read_b128 v[54:57], v89 offset:18688
	v_add_f32_dpp v0, v0, v0 row_ror:8 row_mask:0xf bank_mask:0xf bound_ctrl:1
	s_waitcnt lgkmcnt(8)
	v_pk_fma_f32 v[38:39], v[38:39], v[0:1], v[58:59] op_sel_hi:[1,0,1] neg_lo:[1,0,0] neg_hi:[1,0,0]
	v_pk_fma_f32 v[40:41], v[40:41], v[0:1], v[60:61] op_sel_hi:[1,0,1] neg_lo:[1,0,0] neg_hi:[1,0,0]
	v_pk_mul_f32 v[26:27], v[26:27], v[38:39]
	v_pk_mul_f32 v[44:45], v[44:45], v[40:41]
	v_pk_mul_f32 v[10:11], v[10:11], v[38:39]
	v_pk_fma_f32 v[38:39], v[42:43], v[38:39], v[44:45]
	v_pk_fma_f32 v[26:27], v[28:29], v[40:41], v[26:27]
	v_pk_fma_f32 v[58:59], v[6:7], v[14:15], v[10:11] op_sel_hi:[0,1,1]
	v_add_f32_e32 v0, v38, v39
	v_add_f32_e32 v10, v26, v27
	ds_write_b32 v88, v0 offset:50176
	v_pk_mul_f32 v[12:13], v[12:13], v[40:41]
	v_add_f32_dpp v0, v10, v10 quad_perm:[1,0,3,2] row_mask:0xf bank_mask:0xf bound_ctrl:1
	v_pk_fma_f32 v[60:61], v[6:7], v[16:17], v[12:13] op_sel_hi:[0,1,1]
	ds_read_b128 v[10:13], v90 offset:2560
	v_add_f32_dpp v0, v0, v0 quad_perm:[2,3,0,1] row_mask:0xf bank_mask:0xf bound_ctrl:1
	ds_read_b128 v[14:17], v89 offset:6656
	ds_read_b128 v[26:29], v90 offset:6656
	v_add_f32_dpp v0, v0, v0 row_half_mirror row_mask:0xf bank_mask:0xf bound_ctrl:1
	ds_read_b128 v[38:41], v90 offset:10752
	ds_read_b128 v[42:45], v89 offset:18944
	v_add_f32_dpp v0, v0, v0 row_ror:8 row_mask:0xf bank_mask:0xf bound_ctrl:1
	s_waitcnt lgkmcnt(8)
	v_pk_fma_f32 v[30:31], v[30:31], v[0:1], v[58:59] op_sel_hi:[1,0,1] neg_lo:[1,0,0] neg_hi:[1,0,0]
	v_pk_fma_f32 v[32:33], v[32:33], v[0:1], v[60:61] op_sel_hi:[1,0,1] neg_lo:[1,0,0] neg_hi:[1,0,0]
	v_pk_mul_f32 v[34:35], v[34:35], v[30:31]
	v_pk_mul_f32 v[48:49], v[48:49], v[32:33]
	v_pk_mul_f32 v[18:19], v[18:19], v[30:31]
	v_pk_mul_f32 v[20:21], v[20:21], v[32:33]
	v_pk_fma_f32 v[30:31], v[46:47], v[30:31], v[48:49]
	v_pk_fma_f32 v[32:33], v[36:37], v[32:33], v[34:35]
	v_pk_fma_f32 v[58:59], v[6:7], v[22:23], v[18:19] op_sel:[1,0,0]
	v_add_f32_e32 v0, v30, v31
	v_add_f32_e32 v18, v32, v33
	ds_write_b32 v88, v0 offset:51200
	v_pk_fma_f32 v[6:7], v[6:7], v[24:25], v[20:21] op_sel:[1,0,0]
	v_add_f32_dpp v0, v18, v18 quad_perm:[1,0,3,2] row_mask:0xf bank_mask:0xf bound_ctrl:1
	ds_read_b128 v[18:21], v90 offset:2816
	ds_read_b128 v[22:25], v89 offset:6912
	v_add_f32_dpp v0, v0, v0 quad_perm:[2,3,0,1] row_mask:0xf bank_mask:0xf bound_ctrl:1
	ds_read_b128 v[30:33], v90 offset:6912
	ds_read_b128 v[34:37], v90 offset:11008
	v_add_f32_dpp v0, v0, v0 row_half_mirror row_mask:0xf bank_mask:0xf bound_ctrl:1
	ds_read_b128 v[46:49], v89 offset:19200
	s_nop 0
	v_add_f32_dpp v0, v0, v0 row_ror:8 row_mask:0xf bank_mask:0xf bound_ctrl:1
	s_waitcnt lgkmcnt(8)
	v_pk_fma_f32 v[50:51], v[50:51], v[0:1], v[58:59] op_sel_hi:[1,0,1] neg_lo:[1,0,0] neg_hi:[1,0,0]
	v_pk_fma_f32 v[6:7], v[52:53], v[0:1], v[6:7] op_sel_hi:[1,0,1] neg_lo:[1,0,0] neg_hi:[1,0,0]
	v_pk_mul_f32 v[26:27], v[26:27], v[50:51]
	v_pk_mul_f32 v[52:53], v[56:57], v[6:7]
	v_pk_mul_f32 v[10:11], v[10:11], v[50:51]
	v_pk_mul_f32 v[12:13], v[12:13], v[6:7]
	v_pk_fma_f32 v[50:51], v[54:55], v[50:51], v[52:53]
	v_pk_fma_f32 v[6:7], v[28:29], v[6:7], v[26:27]
	v_add_f32_e32 v0, v50, v51
	v_add_f32_e32 v6, v6, v7
	ds_write_b32 v88, v0 offset:52224
	v_pk_fma_f32 v[54:55], v[8:9], v[14:15], v[10:11] op_sel_hi:[0,1,1]
	v_add_f32_dpp v0, v6, v6 quad_perm:[1,0,3,2] row_mask:0xf bank_mask:0xf bound_ctrl:1
	v_pk_fma_f32 v[56:57], v[8:9], v[16:17], v[12:13] op_sel_hi:[0,1,1]
	ds_read_b128 v[6:9], v90 offset:3072
	v_add_f32_dpp v0, v0, v0 quad_perm:[2,3,0,1] row_mask:0xf bank_mask:0xf bound_ctrl:1
	ds_read_b128 v[10:13], v89 offset:7168
	ds_read_b128 v[14:17], v90 offset:7168
	v_add_f32_dpp v0, v0, v0 row_half_mirror row_mask:0xf bank_mask:0xf bound_ctrl:1
	ds_read_b128 v[26:29], v90 offset:11264
	ds_read_b128 v[50:53], v89 offset:19456
	v_add_f32_dpp v0, v0, v0 row_ror:8 row_mask:0xf bank_mask:0xf bound_ctrl:1
	s_waitcnt lgkmcnt(8)
	v_pk_fma_f32 v[38:39], v[38:39], v[0:1], v[54:55] op_sel_hi:[1,0,1] neg_lo:[1,0,0] neg_hi:[1,0,0]
	v_pk_fma_f32 v[40:41], v[40:41], v[0:1], v[56:57] op_sel_hi:[1,0,1] neg_lo:[1,0,0] neg_hi:[1,0,0]
	v_pk_mul_f32 v[30:31], v[30:31], v[38:39]
	v_pk_mul_f32 v[44:45], v[44:45], v[40:41]
	v_pk_mul_f32 v[18:19], v[18:19], v[38:39]
	v_pk_fma_f32 v[38:39], v[42:43], v[38:39], v[44:45]
	v_pk_fma_f32 v[30:31], v[32:33], v[40:41], v[30:31]
	v_pk_fma_f32 v[54:55], v[84:85], v[22:23], v[18:19] op_sel_hi:[0,1,1]
	v_add_f32_e32 v0, v38, v39
	v_add_f32_e32 v18, v30, v31
	ds_write_b32 v88, v0 offset:53248
	v_pk_mul_f32 v[20:21], v[20:21], v[40:41]
	v_add_f32_dpp v0, v18, v18 quad_perm:[1,0,3,2] row_mask:0xf bank_mask:0xf bound_ctrl:1
	v_pk_fma_f32 v[56:57], v[84:85], v[24:25], v[20:21] op_sel_hi:[0,1,1]
	ds_read_b128 v[18:21], v90 offset:3328
	v_add_f32_dpp v0, v0, v0 quad_perm:[2,3,0,1] row_mask:0xf bank_mask:0xf bound_ctrl:1
	ds_read_b128 v[22:25], v89 offset:7424
	ds_read_b128 v[30:33], v90 offset:7424
	v_add_f32_dpp v0, v0, v0 row_half_mirror row_mask:0xf bank_mask:0xf bound_ctrl:1
	ds_read_b128 v[38:41], v90 offset:11520
	ds_read_b128 v[42:45], v89 offset:19712
	v_add_f32_dpp v0, v0, v0 row_ror:8 row_mask:0xf bank_mask:0xf bound_ctrl:1
	s_waitcnt lgkmcnt(8)
	v_pk_fma_f32 v[34:35], v[34:35], v[0:1], v[54:55] op_sel_hi:[1,0,1] neg_lo:[1,0,0] neg_hi:[1,0,0]
	v_pk_fma_f32 v[36:37], v[36:37], v[0:1], v[56:57] op_sel_hi:[1,0,1] neg_lo:[1,0,0] neg_hi:[1,0,0]
	v_pk_mul_f32 v[14:15], v[14:15], v[34:35]
	v_pk_mul_f32 v[48:49], v[48:49], v[36:37]
	v_pk_mul_f32 v[6:7], v[6:7], v[34:35]
	v_pk_fma_f32 v[34:35], v[46:47], v[34:35], v[48:49]
	v_pk_fma_f32 v[14:15], v[16:17], v[36:37], v[14:15]
	v_pk_fma_f32 v[54:55], v[2:3], v[10:11], v[6:7] op_sel_hi:[0,1,1]
	v_add_f32_e32 v0, v34, v35
	v_add_f32_e32 v6, v14, v15
	ds_write_b32 v88, v0 offset:54272
	v_pk_mul_f32 v[8:9], v[8:9], v[36:37]
	v_add_f32_dpp v0, v6, v6 quad_perm:[1,0,3,2] row_mask:0xf bank_mask:0xf bound_ctrl:1
	v_pk_fma_f32 v[56:57], v[2:3], v[12:13], v[8:9] op_sel_hi:[0,1,1]
	ds_read_b128 v[6:9], v90 offset:3584
	v_add_f32_dpp v0, v0, v0 quad_perm:[2,3,0,1] row_mask:0xf bank_mask:0xf bound_ctrl:1
	ds_read_b128 v[10:13], v89 offset:7680
	ds_read_b128 v[14:17], v90 offset:7680
	v_add_f32_dpp v0, v0, v0 row_half_mirror row_mask:0xf bank_mask:0xf bound_ctrl:1
	ds_read_b128 v[34:37], v90 offset:11776
	ds_read_b128 v[46:49], v89 offset:19968
	v_add_f32_dpp v0, v0, v0 row_ror:8 row_mask:0xf bank_mask:0xf bound_ctrl:1
	s_waitcnt lgkmcnt(8)
	v_pk_fma_f32 v[26:27], v[26:27], v[0:1], v[54:55] op_sel_hi:[1,0,1] neg_lo:[1,0,0] neg_hi:[1,0,0]
	v_pk_fma_f32 v[28:29], v[28:29], v[0:1], v[56:57] op_sel_hi:[1,0,1] neg_lo:[1,0,0] neg_hi:[1,0,0]
	v_pk_mul_f32 v[30:31], v[30:31], v[26:27]
	v_pk_mul_f32 v[52:53], v[52:53], v[28:29]
	v_pk_mul_f32 v[18:19], v[18:19], v[26:27]
	v_pk_mul_f32 v[20:21], v[20:21], v[28:29]
	v_pk_fma_f32 v[26:27], v[50:51], v[26:27], v[52:53]
	v_pk_fma_f32 v[28:29], v[32:33], v[28:29], v[30:31]
	v_pk_fma_f32 v[54:55], v[2:3], v[22:23], v[18:19] op_sel:[1,0,0]
	v_add_f32_e32 v0, v26, v27
	v_add_f32_e32 v18, v28, v29
	ds_write_b32 v88, v0 offset:55296
	v_pk_fma_f32 v[2:3], v[2:3], v[24:25], v[20:21] op_sel:[1,0,0]
	v_add_f32_dpp v0, v18, v18 quad_perm:[1,0,3,2] row_mask:0xf bank_mask:0xf bound_ctrl:1
	ds_read_b128 v[18:21], v90 offset:3840
	ds_read_b128 v[22:25], v89 offset:7936
	v_add_f32_dpp v0, v0, v0 quad_perm:[2,3,0,1] row_mask:0xf bank_mask:0xf bound_ctrl:1
	ds_read_b128 v[26:29], v90 offset:7936
	ds_read_b128 v[30:33], v90 offset:12032
	v_add_f32_dpp v0, v0, v0 row_half_mirror row_mask:0xf bank_mask:0xf bound_ctrl:1
	ds_read_b128 v[50:53], v89 offset:20224
	s_nop 0
	v_add_f32_dpp v0, v0, v0 row_ror:8 row_mask:0xf bank_mask:0xf bound_ctrl:1
	s_waitcnt lgkmcnt(13)
	v_pk_fma_f32 v[38:39], v[38:39], v[0:1], v[54:55] op_sel_hi:[1,0,1] neg_lo:[1,0,0] neg_hi:[1,0,0]
	v_pk_fma_f32 v[2:3], v[40:41], v[0:1], v[2:3] op_sel_hi:[1,0,1] neg_lo:[1,0,0] neg_hi:[1,0,0]
	s_waitcnt lgkmcnt(8)
	v_pk_mul_f32 v[14:15], v[14:15], v[38:39]
	v_pk_mul_f32 v[40:41], v[44:45], v[2:3]
	v_pk_mul_f32 v[8:9], v[8:9], v[2:3]
	v_pk_fma_f32 v[2:3], v[16:17], v[2:3], v[14:15]
	v_pk_mul_f32 v[6:7], v[6:7], v[38:39]
	v_add_f32_e32 v0, v2, v3
	v_pk_fma_f32 v[6:7], v[4:5], v[10:11], v[6:7] op_sel_hi:[0,1,1]
	v_pk_fma_f32 v[4:5], v[4:5], v[12:13], v[8:9] op_sel_hi:[0,1,1]
	v_add_f32_dpp v0, v0, v0 quad_perm:[1,0,3,2] row_mask:0xf bank_mask:0xf bound_ctrl:1
	v_pk_fma_f32 v[38:39], v[42:43], v[38:39], v[40:41]
	s_nop 0
	v_add_f32_dpp v0, v0, v0 quad_perm:[2,3,0,1] row_mask:0xf bank_mask:0xf bound_ctrl:1
	v_add_f32_e32 v14, v38, v39
	s_nop 0
	v_add_f32_dpp v0, v0, v0 row_half_mirror row_mask:0xf bank_mask:0xf bound_ctrl:1
	s_nop 1
	v_add_f32_dpp v0, v0, v0 row_ror:8 row_mask:0xf bank_mask:0xf bound_ctrl:1
	s_waitcnt lgkmcnt(7)
	v_pk_fma_f32 v[2:3], v[34:35], v[0:1], v[6:7] op_sel_hi:[1,0,1] neg_lo:[1,0,0] neg_hi:[1,0,0]
	v_pk_fma_f32 v[4:5], v[36:37], v[0:1], v[4:5] op_sel_hi:[1,0,1] neg_lo:[1,0,0] neg_hi:[1,0,0]
	s_waitcnt lgkmcnt(2)
	v_pk_mul_f32 v[8:9], v[26:27], v[2:3]
	v_pk_mul_f32 v[6:7], v[48:49], v[4:5]
	v_pk_mul_f32 v[10:11], v[18:19], v[2:3]
	v_pk_mul_f32 v[12:13], v[20:21], v[4:5]
	v_pk_fma_f32 v[2:3], v[46:47], v[2:3], v[6:7]
	v_pk_fma_f32 v[4:5], v[28:29], v[4:5], v[8:9]
	v_add_f32_e32 v0, v2, v3
	v_add_f32_e32 v2, v4, v5
	ds_write2st64_b32 v88, v14, v0 offset0:220 offset1:224
	v_pk_fma_f32 v[8:9], v[86:87], v[24:25], v[12:13] op_sel_hi:[0,1,1]
	v_add_f32_dpp v0, v2, v2 quad_perm:[1,0,3,2] row_mask:0xf bank_mask:0xf bound_ctrl:1
	v_pk_fma_f32 v[6:7], v[86:87], v[22:23], v[10:11] op_sel_hi:[0,1,1]
	s_nop 0
	v_add_f32_dpp v0, v0, v0 quad_perm:[2,3,0,1] row_mask:0xf bank_mask:0xf bound_ctrl:1
	s_nop 1
	v_add_f32_dpp v0, v0, v0 row_half_mirror row_mask:0xf bank_mask:0xf bound_ctrl:1
	s_nop 1
	v_add_f32_dpp v0, v0, v0 row_ror:8 row_mask:0xf bank_mask:0xf bound_ctrl:1
	s_waitcnt lgkmcnt(2)
	v_pk_fma_f32 v[76:77], v[32:33], v[0:1], v[8:9] op_sel_hi:[1,0,1] neg_lo:[1,0,0] neg_hi:[1,0,0]
	v_pk_fma_f32 v[74:75], v[30:31], v[0:1], v[6:7] op_sel_hi:[1,0,1] neg_lo:[1,0,0] neg_hi:[1,0,0]
	s_waitcnt lgkmcnt(1)
	v_pk_mul_f32 v[2:3], v[52:53], v[76:77]
	s_nop 0
	v_pk_fma_f32 v[2:3], v[50:51], v[74:75], v[2:3]
	s_nop 0
	v_add_f32_e32 v0, v2, v3
	ds_write_b32 v88, v0 offset:58368
	s_waitcnt lgkmcnt(0)
	s_barrier
	s_cbranch_scc0 .LBB0_1050
	s_setprio 0
.LBB0_1051:
	s_andn2_saveexec_b64 s[14:15], s[24:25]
	s_cbranch_execz .LBB0_1278
	v_and_b32_e32 v123, 0xc0, v232
	v_lshlrev_b32_e32 v123, 4, v123
	v_mov_b32_e32 v122, 0x20200
	s_lshl_b32 s2, s30, 2
	s_and_b32 s33, s2, 28
	s_ashr_i32 s2, s30, 5
	s_add_i32 s33, s33, s2
	s_ashr_i32 s3, s33, 3
	s_and_b32 s37, s2, 1
	s_cmp_eq_u32 s37, 0
	s_cselect_b64 s[16:17], -1, 0
	s_cmp_eq_u32 s37, 1
	s_cselect_b64 s[34:35], -1, 0
	s_lshl_b32 s24, s3, 12
	s_lshl_b32 s61, s3, 8
	v_add_u32_e32 v39, 0xffffff00, v4
	s_movk_i32 s2, 0xfff
	s_add_i32 s31, s24, 0x10ff
	s_add_i32 s43, s61, 0x40ff
	v_lshrrev_b32_e32 v55, 4, v39
	v_cmp_lt_u32_e64 s[44:45], s2, v39
	s_mov_b64 s[26:27], -1
	s_and_b64 vcc, exec, s[34:35]
	s_cbranch_vccz .LBB0_1058
	s_and_saveexec_b64 s[26:27], s[44:45]
	s_xor_b64 s[26:27], exec, s[26:27]
	v_sub_u32_e32 v2, s31, v55
	s_andn2_saveexec_b64 s[26:27], s[26:27]
	v_sub_u32_e32 v2, s43, v55
	s_or_b64 exec, exec, s[26:27]
	s_mov_b64 s[26:27], 0

.LBB0_1064:
	s_lshl_b32 s2, s33, 5
	v_ashrrev_i32_e32 v3, 31, v2
	s_and_b32 s60, s2, 0xc0
	s_lshl_b32 s2, s30, 1
	v_lshlrev_b64 v[10:11], 1, v[2:3]
	s_and_b32 s33, s2, 48
	v_or_b32_e32 v10, s37, v10
	v_readlane_b32 s2, v252, 0
	v_lshlrev_b64 v[14:15], 10, v[10:11]
	v_readlane_b32 s3, v252, 1
	v_lshlrev_b32_e32 v5, 2, v39
	v_and_or_b32 v12, v5, 60, s60
	v_lshl_add_u64 v[6:7], s[2:3], 0, v[14:15]
	v_readlane_b32 s2, v252, 6
	v_lshlrev_b64 v[10:11], 9, v[10:11]
	v_readlane_b32 s3, v252, 7
	v_lshlrev_b32_e32 v40, 1, v12
	v_mov_b32_e32 v41, v1
	v_lshl_add_u64 v[10:11], s[2:3], 0, v[10:11]
	v_lshl_add_u64 v[10:11], v[10:11], 0, v[40:41]
	v_readlane_b32 s2, v252, 20
	global_load_dwordx2 v[18:19], v[10:11], off
	v_lshlrev_b64 v[10:11], 10, v[2:3]
	v_readlane_b32 s3, v252, 21
	v_lshlrev_b64 v[2:3], 9, v[2:3]
	v_lshlrev_b32_e32 v0, 2, v12
	v_lshl_add_u64 v[10:11], s[2:3], 0, v[10:11]
	v_readlane_b32 s2, v252, 22
	v_readlane_b32 s3, v252, 23
	v_lshl_add_u64 v[6:7], v[6:7], 0, v[0:1]
	v_add_u32_e32 v124, 0x12800, v123
	s_nop 0
	v_readfirstlane_b32 s98, v124
	s_mov_b32 m0, s98
	s_nop 0
	global_load_lds_dwordx4 v[6:7], off
	v_lshl_add_u64 v[14:15], s[2:3], 0, v[14:15]
	v_readlane_b32 s2, v252, 8
	v_readlane_b32 s3, v252, 9
	v_lshl_add_u64 v[10:11], v[10:11], 0, v[0:1]
	v_add_u32_e32 v124, 0x13800, v123
	s_nop 0
	v_readfirstlane_b32 s98, v124
	s_mov_b32 m0, s98
	s_nop 0
	global_load_lds_dwordx4 v[10:11], off
	v_lshl_add_u64 v[2:3], s[2:3], 0, v[2:3]
	v_lshl_add_u64 v[2:3], v[2:3], 0, v[40:41]
	global_load_dwordx2 v[20:21], v[2:3], off
	v_lshl_add_u64 v[14:15], v[14:15], 0, v[0:1]
	v_add_u32_e32 v124, 0x14800, v123
	s_nop 0
	v_readfirstlane_b32 s98, v124
	s_mov_b32 m0, s98
	s_nop 0
	global_load_lds_dwordx4 v[14:15], off
	v_lshlrev_b32_e32 v2, 4, v39
	v_and_b32_e32 v91, 0xffffff00, v2
	v_and_b32_e32 v92, 0xf0, v2
	v_bfe_u32 v90, v4, 2, 4
	v_and_b32_e32 v22, 12, v5
	v_add3_u32 v23, 0, v91, v92
	v_cmp_gt_u32_e64 s[44:45], 64, v39
	v_lshlrev_b32_e32 v42, 1, v22
	s_waitcnt vmcnt(4)
	v_lshlrev_b32_e32 v2, 16, v18
	v_and_b32_e32 v3, 0xffff0000, v18
	v_lshlrev_b32_e32 v4, 16, v19
	v_and_b32_e32 v5, 0xffff0000, v19
	s_waitcnt vmcnt(3)
	ds_write_b128 v23, v[2:5] offset:4096
	s_waitcnt vmcnt(2)
	s_waitcnt vmcnt(0)
	v_lshlrev_b32_e32 v2, 16, v20
	v_and_b32_e32 v3, 0xffff0000, v20
	v_lshlrev_b32_e32 v4, 16, v21
	v_and_b32_e32 v5, 0xffff0000, v21
	ds_write_b128 v23, v[2:5] offset:16384
	s_and_saveexec_b64 s[26:27], s[44:45]
	s_cbranch_execz .LBB0_1066
	v_or_b32_e32 v2, s25, v90
	v_sub_u32_e32 v3, s43, v90
	v_cndmask_b32_e64 v2, v3, v2, s[16:17]
	v_ashrrev_i32_e32 v3, 31, v2
	v_readlane_b32 s2, v252, 10
	v_lshlrev_b64 v[2:3], 9, v[2:3]
	v_readlane_b32 s3, v252, 11
	s_lshl_b32 s20, s60, 1
	v_mov_b32_e32 v43, v1
	v_lshl_add_u64 v[2:3], s[2:3], 0, v[2:3]
	v_lshl_add_u64 v[2:3], v[2:3], 0, s[20:21]
	s_lshl_b32 s20, s33, 1
	v_lshl_add_u64 v[2:3], v[2:3], 0, s[20:21]
	v_lshl_add_u64 v[2:3], v[2:3], 0, v[42:43]
	global_load_dwordx2 v[2:3], v[2:3], off
	v_lshlrev_b32_e32 v6, 8, v39
	v_and_b32_e32 v6, 0x300, v6
	v_and_b32_e32 v7, -4, v39
	v_add3_u32 v6, 0, v6, v7
	v_add_u32_e32 v6, 0x5000, v6
	s_waitcnt vmcnt(0)
	v_lshlrev_b32_e32 v4, 16, v2
	v_and_b32_e32 v2, 0xffff0000, v2
	v_lshlrev_b32_e32 v5, 16, v3
	v_and_b32_e32 v3, 0xffff0000, v3
	ds_write2_b32 v6, v4, v2 offset1:16
	ds_write2_b32 v6, v5, v3 offset0:32 offset1:48

.LBB0_1078:
	v_ashrrev_i32_e32 v15, 31, v14
	v_lshlrev_b64 v[2:3], 1, v[14:15]
	v_or_b32_e32 v2, s37, v2
	v_readlane_b32 s2, v252, 0
	v_lshlrev_b64 v[6:7], 10, v[2:3]
	v_readlane_b32 s3, v252, 1
	v_lshlrev_b64 v[2:3], 9, v[2:3]
	v_mov_b32_e32 v41, v1
	v_lshl_add_u64 v[4:5], s[2:3], 0, v[6:7]
	v_readlane_b32 s2, v252, 6
	v_readlane_b32 s3, v252, 7
	v_lshl_add_u64 v[4:5], v[4:5], 0, v[0:1]
	v_or_b32_e32 v16, s48, v90
	v_lshl_add_u64 v[2:3], s[2:3], 0, v[2:3]
	v_lshl_add_u64 v[8:9], v[2:3], 0, v[40:41]
	v_readlane_b32 s2, v252, 20
	v_add_u32_e32 v124, 0x15800, v123
	s_nop 0
	v_readfirstlane_b32 s98, v124
	s_mov_b32 m0, s98
	s_nop 0
	global_load_lds_dwordx4 v[4:5], off
	s_nop 0
	global_load_dwordx2 v[56:57], v[8:9], off
	v_lshlrev_b64 v[8:9], 10, v[14:15]
	v_readlane_b32 s3, v252, 21
	v_sub_u32_e32 v17, s38, v90
	v_lshlrev_b64 v[14:15], 9, v[14:15]
	v_lshl_add_u64 v[8:9], s[2:3], 0, v[8:9]
	v_readlane_b32 s2, v252, 22
	v_readlane_b32 s3, v252, 23
	v_cndmask_b32_e64 v16, v17, v16, s[16:17]
	v_ashrrev_i32_e32 v17, 31, v16
	v_lshl_add_u64 v[6:7], s[2:3], 0, v[6:7]
	v_readlane_b32 s2, v252, 8
	v_readlane_b32 s3, v252, 9
	v_lshlrev_b64 v[16:17], 9, v[16:17]
	s_lshl_b32 s26, s60, 1
	v_lshl_add_u64 v[14:15], s[2:3], 0, v[14:15]
	v_readlane_b32 s2, v252, 10
	v_readlane_b32 s3, v252, 11
	s_mov_b32 s27, s21
	s_lshl_b32 s48, s33, 1
	v_lshl_add_u64 v[16:17], s[2:3], 0, v[16:17]
	v_lshl_add_u64 v[16:17], v[16:17], 0, s[26:27]
	s_mov_b32 s49, s21
	v_lshl_add_u64 v[8:9], v[8:9], 0, v[0:1]
	v_lshl_add_u64 v[10:11], v[6:7], 0, v[0:1]
	v_lshl_add_u64 v[14:15], v[14:15], 0, v[40:41]
	v_lshl_add_u64 v[16:17], v[16:17], 0, s[48:49]
	v_mov_b32_e32 v43, v1
	v_add_u32_e32 v124, 0x16800, v123
	s_nop 0
	v_readfirstlane_b32 s98, v124
	s_mov_b32 m0, s98
	s_nop 0
	global_load_lds_dwordx4 v[8:9], off
	s_nop 0
	v_add_u32_e32 v124, 0x17800, v123
	s_nop 0
	v_readfirstlane_b32 s98, v124
	s_mov_b32 m0, s98
	s_nop 0
	global_load_lds_dwordx4 v[10:11], off
	v_lshl_add_u64 v[16:17], v[16:17], 0, v[42:43]
	global_load_dwordx2 v[58:59], v[14:15], off
	global_load_dwordx2 v[74:75], v[16:17], off
	s_movk_i32 s2, 0xdff
	s_add_i32 s27, s61, 0x40df
	v_cmp_lt_u32_e64 s[46:47], s2, v39
	s_mov_b64 s[50:51], -1
	s_and_b64 vcc, exec, s[34:35]
	s_cbranch_vccz .LBB0_1084
	s_and_saveexec_b64 s[50:51], s[46:47]
	s_xor_b64 s[50:51], exec, s[50:51]
	v_sub_u32_e32 v14, s24, v55
	v_add_u32_e32 v26, 0x10df, v14
	s_andn2_saveexec_b64 s[50:51], s[50:51]
	v_sub_u32_e32 v26, s27, v55
	s_or_b64 exec, exec, s[50:51]
	s_mov_b64 s[50:51], 0
	v_readlane_b32 s73, v250, 16

.LBB0_1090:
	v_ashrrev_i32_e32 v27, 31, v26
	v_lshlrev_b64 v[14:15], 1, v[26:27]
	v_or_b32_e32 v14, s37, v14
	v_readlane_b32 s2, v252, 0
	v_lshlrev_b64 v[18:19], 10, v[14:15]
	v_readlane_b32 s3, v252, 1
	v_lshlrev_b64 v[14:15], 9, v[14:15]
	v_mov_b32_e32 v41, v1
	v_lshl_add_u64 v[16:17], s[2:3], 0, v[18:19]
	v_readlane_b32 s2, v252, 6
	v_readlane_b32 s3, v252, 7
	v_lshl_add_u64 v[16:17], v[16:17], 0, v[0:1]
	v_or_b32_e32 v28, s38, v90
	v_lshl_add_u64 v[14:15], s[2:3], 0, v[14:15]
	v_lshl_add_u64 v[20:21], v[14:15], 0, v[40:41]
	v_readlane_b32 s2, v252, 20
	v_add_u32_e32 v124, 0x18800, v123
	s_nop 0
	v_readfirstlane_b32 s98, v124
	s_mov_b32 m0, s98
	s_nop 0
	global_load_lds_dwordx4 v[16:17], off
	s_nop 0
	global_load_dwordx2 v[76:77], v[20:21], off
	v_lshlrev_b64 v[20:21], 10, v[26:27]
	v_readlane_b32 s3, v252, 21
	v_sub_u32_e32 v29, s27, v90
	v_lshlrev_b64 v[26:27], 9, v[26:27]
	v_lshl_add_u64 v[20:21], s[2:3], 0, v[20:21]
	v_readlane_b32 s2, v252, 22
	v_readlane_b32 s3, v252, 23
	v_cndmask_b32_e64 v28, v29, v28, s[16:17]
	v_ashrrev_i32_e32 v29, 31, v28
	v_lshl_add_u64 v[18:19], s[2:3], 0, v[18:19]
	v_readlane_b32 s2, v252, 8
	v_readlane_b32 s3, v252, 9
	v_lshlrev_b64 v[28:29], 9, v[28:29]
	s_mov_b32 s27, s21
	v_lshl_add_u64 v[26:27], s[2:3], 0, v[26:27]
	v_readlane_b32 s2, v252, 10
	v_readlane_b32 s3, v252, 11
	s_mov_b32 s49, s21
	v_lshl_add_u64 v[20:21], v[20:21], 0, v[0:1]
	v_lshl_add_u64 v[28:29], s[2:3], 0, v[28:29]
	v_lshl_add_u64 v[28:29], v[28:29], 0, s[26:27]
	v_lshl_add_u64 v[22:23], v[18:19], 0, v[0:1]
	v_lshl_add_u64 v[26:27], v[26:27], 0, v[40:41]
	v_lshl_add_u64 v[28:29], v[28:29], 0, s[48:49]
	v_mov_b32_e32 v43, v1
	v_add_u32_e32 v124, 0x19800, v123
	s_nop 0
	v_readfirstlane_b32 s98, v124
	s_mov_b32 m0, s98
	s_nop 0
	global_load_lds_dwordx4 v[20:21], off
	s_nop 0
	v_add_u32_e32 v124, 0x1a800, v123
	s_nop 0
	v_readfirstlane_b32 s98, v124
	s_mov_b32 m0, s98
	s_nop 0
	global_load_lds_dwordx4 v[22:23], off
	v_lshl_add_u64 v[28:29], v[28:29], 0, v[42:43]
	global_load_dwordx2 v[78:79], v[26:27], off
	global_load_dwordx2 v[80:81], v[28:29], off
	s_movk_i32 s2, 0xcff
	s_add_i32 s27, s61, 0x40cf
	v_cmp_lt_u32_e64 s[46:47], s2, v39
	s_mov_b64 s[50:51], -1
	s_and_b64 vcc, exec, s[34:35]
	s_cbranch_vccz .LBB0_1096
	s_and_saveexec_b64 s[50:51], s[46:47]
	s_xor_b64 s[50:51], exec, s[50:51]
	v_sub_u32_e32 v26, s24, v55
	v_add_u32_e32 v44, 0x10cf, v26
	s_andn2_saveexec_b64 s[50:51], s[50:51]
	v_sub_u32_e32 v44, s27, v55
	s_or_b64 exec, exec, s[50:51]
	s_mov_b64 s[50:51], 0
	v_readlane_b32 s73, v250, 16

.LBB0_1102:
	v_ashrrev_i32_e32 v45, 31, v44
	v_lshlrev_b64 v[26:27], 1, v[44:45]
	v_or_b32_e32 v26, s37, v26
	v_readlane_b32 s2, v252, 0
	v_readlane_b32 s4, v252, 6
	v_or_b32_e32 v43, s61, v90
	v_sub_u32_e32 v46, s27, v90
	v_lshlrev_b64 v[30:31], 10, v[26:27]
	v_readlane_b32 s3, v252, 1
	v_lshlrev_b64 v[26:27], 9, v[26:27]
	v_readlane_b32 s5, v252, 7
	v_cndmask_b32_e64 v46, v46, v43, s[16:17]
	v_lshl_add_u64 v[28:29], s[2:3], 0, v[30:31]
	v_lshl_add_u64 v[26:27], s[4:5], 0, v[26:27]
	v_mov_b32_e32 v41, v1
	v_ashrrev_i32_e32 v47, 31, v46
	v_readlane_b32 s8, v252, 10
	v_lshl_add_u64 v[28:29], v[28:29], 0, v[0:1]
	v_lshl_add_u64 v[32:33], v[26:27], 0, v[40:41]
	v_readlane_b32 s10, v252, 20
	v_readlane_b32 s12, v252, 22
	v_readlane_b32 s6, v252, 8
	v_lshlrev_b64 v[46:47], 9, v[46:47]
	v_readlane_b32 s9, v252, 11
	v_add_u32_e32 v124, 0x1b800, v123
	s_nop 0
	v_readfirstlane_b32 s98, v124
	s_mov_b32 m0, s98
	s_nop 0
	global_load_lds_dwordx4 v[28:29], off
	s_nop 0
	global_load_dwordx2 v[82:83], v[32:33], off
	v_lshlrev_b64 v[32:33], 10, v[44:45]
	v_readlane_b32 s11, v252, 21
	v_readlane_b32 s13, v252, 23
	v_lshlrev_b64 v[44:45], 9, v[44:45]
	v_readlane_b32 s7, v252, 9
	v_lshl_add_u64 v[46:47], s[8:9], 0, v[46:47]
	s_mov_b32 s27, s21
	v_lshl_add_u64 v[32:33], s[10:11], 0, v[32:33]
	v_lshl_add_u64 v[30:31], s[12:13], 0, v[30:31]
	v_lshl_add_u64 v[44:45], s[6:7], 0, v[44:45]
	v_lshl_add_u64 v[46:47], v[46:47], 0, s[26:27]
	s_mov_b32 s49, s21
	v_lshl_add_u64 v[32:33], v[32:33], 0, v[0:1]
	v_lshl_add_u64 v[34:35], v[30:31], 0, v[0:1]
	v_lshl_add_u64 v[44:45], v[44:45], 0, v[40:41]
	v_lshl_add_u64 v[46:47], v[46:47], 0, s[48:49]
	v_mov_b32_e32 v43, v1
	v_add_u32_e32 v124, 0x1c800, v123
	s_nop 0
	v_readfirstlane_b32 s98, v124
	s_mov_b32 m0, s98
	s_nop 0
	global_load_lds_dwordx4 v[32:33], off
	s_nop 0
	v_add_u32_e32 v124, 0x1d800, v123
	s_nop 0
	v_readfirstlane_b32 s98, v124
	s_mov_b32 m0, s98
	s_nop 0
	global_load_lds_dwordx4 v[34:35], off
	v_lshl_add_u64 v[46:47], v[46:47], 0, v[42:43]
	global_load_dwordx2 v[84:85], v[44:45], off
	global_load_dwordx2 v[86:87], v[46:47], off
	s_lshl_b32 s20, s37, 10
	v_lshl_add_u64 v[60:61], s[2:3], 0, v[0:1]
	s_add_u32 s2, s8, s26
	s_addc_u32 s3, s9, 0
	s_add_u32 s26, s2, s48
	s_addc_u32 s27, s3, 0
	v_readlane_b32 s2, v252, 14
	v_readlane_b32 s3, v252, 15
	s_add_u32 s2, s2, s20
	s_addc_u32 s3, s3, 0
	s_lshl_b32 s48, s60, 2
	s_add_u32 s2, s2, s48
	s_addc_u32 s3, s3, 0
	s_lshl_b32 s50, s33, 2
	s_waitcnt lgkmcnt(0)
	s_barrier
	v_lshl_add_u64 v[70:71], s[26:27], 0, v[42:43]
	s_add_u32 s26, s2, s50
	v_lshl_add_u64 v[64:65], s[10:11], 0, v[0:1]
	v_lshl_add_u64 v[66:67], s[12:13], 0, v[0:1]
	v_lshlrev_b32_e32 v0, 6, v39
	v_lshrrev_b32_e32 v94, 2, v39
	s_addc_u32 s27, s3, 0
	v_mov_b32_e32 v39, v1
	v_lshl_add_u64 v[62:63], s[4:5], 0, v[40:41]
	v_lshl_add_u64 v[68:69], s[6:7], 0, v[40:41]
	v_and_b32_e32 v93, 0xc0, v0
	v_add_u32_e32 v0, 0, v0
	v_lshl_add_u64 v[72:73], s[26:27], 0, v[38:39]
	s_sub_i32 s98, 1, s37
	s_sub_i32 s98, s98, s37
	s_ashr_i32 s99, s98, 31
	v_mov_b32_e32 v112, s98
	v_mov_b32_e32 v113, s99
	s_cmp_eq_u32 s37, 0
	s_cselect_b32 s98, 64, 0xbf
	s_add_i32 s98, s98, s25
	v_mov_b32_e32 v110, s98
	v_mad_i32_i24 v111, v55, v112, v110
	v_and_b32_e32 v108, 63, v232
	v_lshrrev_b32_e32 v108, 2, v108
	v_mad_i32_i24 v109, v108, v112, v110
	v_lshl_or_b32 v108, v111, 1, s37
	s_movk_i32 s98, 0x400
	s_movk_i32 s99, 0x200
	v_mad_u64_u32 v[96:97], vcc, v108, s98, v[60:61]
	v_mad_u64_u32 v[98:99], vcc, v108, s99, v[62:63]
	v_mad_u64_u32 v[100:101], vcc, v111, s98, v[64:65]
	v_mad_u64_u32 v[102:103], vcc, v108, s98, v[66:67]
	v_mad_u64_u32 v[104:105], vcc, v111, s99, v[68:69]
	v_mad_u64_u32 v[106:107], vcc, v109, s99, v[70:71]
	s_cmp_eq_u32 s37, 0
	s_cselect_b32 s98, 0, 0xff
	s_add_i32 s98, s98, s25
	v_mov_b32_e32 v110, s98
	v_mad_i32_i24 v111, v55, v112, v110
	s_movk_i32 s98, 0x800
	v_mad_u64_u32 v[108:109], vcc, v111, s98, v[72:73]
	s_sub_i32 s98, s24, s25
	s_movk_i32 s99, 0x1000
	s_cmp_eq_u32 s37, 0
	s_cselect_b32 s99, 0xffffff00, s99
	s_add_i32 s98, s98, s99
	s_lshl_b32 s98, s98, 9
	s_ashr_i32 s99, s98, 31
	v_mov_b32_e32 v120, s98
	v_mov_b32_e32 v121, s99
	s_lshl_b32 s98, s98, 1
	v_mov_b32_e32 v118, s98
	v_mov_b32_e32 v119, s99
	s_lshl_b32 s98, s98, 1
	v_mov_b32_e32 v110, s98
	v_mov_b32_e32 v111, s99
	v_lshlrev_b32_e32 v112, 15, v112
	v_ashrrev_i32_e32 v114, 1, v112
	v_mov_b32_e32 v115, v113
	v_ashrrev_i32_e32 v116, 2, v112
	v_mov_b32_e32 v117, v113
	s_mov_b32 s49, 0
	s_mov_b32 s51, 0
	s_branch .LBB0_1106

.Lscan_ld_steady_a:
	v_add_u32_e32 v38, s72, v91
	v_add_u32_e32 v95, v38, v92
	s_waitcnt vmcnt(19)
	v_lshlrev_b32_e32 v38, 16, v56
	v_and_b32_e32 v39, 0xffff0000, v56
	v_lshlrev_b32_e32 v40, 16, v57
	v_and_b32_e32 v41, 0xffff0000, v57
	ds_write_b128 v95, v[38:41] offset:4096
	s_waitcnt vmcnt(18)
	s_waitcnt vmcnt(17)
	s_waitcnt vmcnt(16)
	v_lshlrev_b32_e32 v38, 16, v58
	v_and_b32_e32 v39, 0xffff0000, v58
	v_lshlrev_b32_e32 v40, 16, v59
	v_and_b32_e32 v41, 0xffff0000, v59
	ds_write_b128 v95, v[38:41] offset:16384
	s_and_saveexec_b64 s[26:27], s[44:45]
	s_cbranch_execz .LBB0_1109
	v_lshlrev_b32_e32 v42, 2, v93
	v_lshlrev_b32_e32 v43, 2, v94
	v_add3_u32 v42, s72, v42, v43
	s_waitcnt vmcnt(15)
	v_lshlrev_b32_e32 v38, 16, v74
	v_and_b32_e32 v39, 0xffff0000, v74
	v_add_u32_e32 v42, 0x5000, v42
	v_lshlrev_b32_e32 v40, 16, v75
	v_and_b32_e32 v41, 0xffff0000, v75
	ds_write2_b32 v42, v38, v39 offset1:16
	ds_write2_b32 v42, v40, v41 offset0:32 offset1:48
	s_or_b64 exec, exec, s[26:27]
	s_cmpk_gt_u32 s49, 0x10b
	s_cbranch_scc0 .LBB0_1110

.Lscan_ld_nofix:
	v_readfirstlane_b32 s2, v122
	v_readfirstlane_b32 s3, v123
	s_add_i32 s3, s3, s2
	s_mov_b32 m0, s3
	s_add_i32 s2, s2, 0x3000
	s_cmp_eq_u32 s2, 0x1e800
	s_cselect_b32 s2, 0x20200, s2
	s_cmp_eq_u32 s2, 0x23200
	s_cselect_b32 s2, 0x12800, s2
	v_mov_b32_e32 v122, s2
	global_load_lds_dwordx4 v[96:97], off
	global_load_dwordx2 v[56:57], v[98:99], off
	s_add_i32 m0, s3, 0x1000
	s_nop 0
	global_load_lds_dwordx4 v[100:101], off
	s_add_i32 m0, s3, 0x2000
	s_nop 0
	global_load_lds_dwordx4 v[102:103], off
	global_load_dwordx2 v[58:59], v[104:105], off
	global_load_dwordx2 v[74:75], v[106:107], off
	v_lshl_add_u64 v[96:97], v[112:113], 0, v[96:97]
	v_lshl_add_u64 v[98:99], v[114:115], 0, v[98:99]
	v_lshl_add_u64 v[100:101], v[114:115], 0, v[100:101]
	v_lshl_add_u64 v[102:103], v[112:113], 0, v[102:103]
	v_lshl_add_u64 v[104:105], v[116:117], 0, v[104:105]
	v_lshl_add_u64 v[106:107], v[116:117], 0, v[106:107]
	s_mov_b64 s[76:77], s[40:41]
	s_cmp_eq_u32 s49, 0
	s_cbranch_scc1 .LBB0_1162

.Lscan_ld_steady_b:
	s_cmpk_lt_u32 s49, 0x10e
	s_cselect_b64 s[60:61], -1, 0
	s_cmpk_gt_u32 s49, 0x10d
	s_cbranch_scc1 .LBB0_1167
	s_bitcmp1_b32 s49, 0
	s_cselect_b32 s2, 0x5400, 0
	s_add_i32 s33, s2, 0
	v_add3_u32 v42, s33, v91, v92
	s_waitcnt vmcnt(19)
	v_lshlrev_b32_e32 v38, 16, v76
	v_and_b32_e32 v39, 0xffff0000, v76
	v_lshlrev_b32_e32 v40, 16, v77
	v_and_b32_e32 v41, 0xffff0000, v77
	ds_write_b128 v42, v[38:41] offset:4096
	s_waitcnt vmcnt(18)
	s_waitcnt vmcnt(17)
	s_waitcnt vmcnt(16)
	v_lshlrev_b32_e32 v38, 16, v78
	v_and_b32_e32 v39, 0xffff0000, v78
	v_lshlrev_b32_e32 v40, 16, v79
	v_and_b32_e32 v41, 0xffff0000, v79
	ds_write_b128 v42, v[38:41] offset:16384
	s_and_saveexec_b64 s[26:27], s[44:45]
	s_cbranch_execz .LBB0_1165
	v_lshlrev_b32_e32 v42, 2, v93
	v_lshlrev_b32_e32 v43, 2, v94
	v_add3_u32 v42, s33, v42, v43
	s_waitcnt vmcnt(15)
	v_lshlrev_b32_e32 v38, 16, v80
	v_and_b32_e32 v39, 0xffff0000, v80
	v_add_u32_e32 v42, 0x5000, v42
	v_lshlrev_b32_e32 v40, 16, v81
	v_and_b32_e32 v41, 0xffff0000, v81
	ds_write2_b32 v42, v38, v39 offset1:16
	ds_write2_b32 v42, v40, v41 offset0:32 offset1:48

.LBB0_1185:
	v_readfirstlane_b32 s2, v122
	v_readfirstlane_b32 s3, v123
	s_add_i32 s3, s3, s2
	s_mov_b32 m0, s3
	s_add_i32 s2, s2, 0x3000
	s_cmp_eq_u32 s2, 0x1e800
	s_cselect_b32 s2, 0x20200, s2
	s_cmp_eq_u32 s2, 0x23200
	s_cselect_b32 s2, 0x12800, s2
	v_mov_b32_e32 v122, s2
	global_load_lds_dwordx4 v[96:97], off
	global_load_dwordx2 v[76:77], v[98:99], off
	s_add_i32 m0, s3, 0x1000
	s_nop 0
	global_load_lds_dwordx4 v[100:101], off
	s_add_i32 m0, s3, 0x2000
	s_nop 0
	global_load_lds_dwordx4 v[102:103], off
	global_load_dwordx2 v[78:79], v[104:105], off
	global_load_dwordx2 v[80:81], v[106:107], off
	v_lshl_add_u64 v[96:97], v[112:113], 0, v[96:97]
	v_lshl_add_u64 v[98:99], v[114:115], 0, v[98:99]
	v_lshl_add_u64 v[100:101], v[114:115], 0, v[100:101]
	v_lshl_add_u64 v[102:103], v[112:113], 0, v[102:103]
	v_lshl_add_u64 v[104:105], v[116:117], 0, v[104:105]
	v_lshl_add_u64 v[106:107], v[116:117], 0, v[106:107]
	s_movk_i32 s79, 0x4400
	v_readlane_b32 s78, v249, 35
	s_mov_b64 s[76:77], s[40:41]
	v_readlane_b32 s71, v250, 15

.Lscan_ld_steady_c:
	s_cbranch_vccnz .LBB0_1105
	s_cmpk_eq_i32 s49, 0x10d
	s_cbranch_scc1 .LBB0_1226
	s_waitcnt vmcnt(19)
	v_lshlrev_b32_e32 v38, 16, v82
	v_and_b32_e32 v39, 0xffff0000, v82
	v_lshlrev_b32_e32 v40, 16, v83
	v_and_b32_e32 v41, 0xffff0000, v83
	ds_write_b128 v95, v[38:41] offset:4096
	s_waitcnt vmcnt(18)
	s_waitcnt vmcnt(17)
	s_waitcnt vmcnt(16)
	v_lshlrev_b32_e32 v38, 16, v84
	v_and_b32_e32 v39, 0xffff0000, v84
	v_lshlrev_b32_e32 v40, 16, v85
	v_and_b32_e32 v41, 0xffff0000, v85
	ds_write_b128 v95, v[38:41] offset:16384
	s_and_saveexec_b64 s[26:27], s[44:45]
	s_cbranch_execz .LBB0_1225
	v_lshlrev_b32_e32 v42, 2, v93
	v_lshlrev_b32_e32 v43, 2, v94
	v_add3_u32 v42, s72, v42, v43
	s_waitcnt vmcnt(15)
	v_lshlrev_b32_e32 v38, 16, v86
	v_and_b32_e32 v39, 0xffff0000, v86
	v_add_u32_e32 v42, 0x5000, v42
	v_lshlrev_b32_e32 v40, 16, v87
	v_and_b32_e32 v41, 0xffff0000, v87
	ds_write2_b32 v42, v38, v39 offset1:16
	ds_write2_b32 v42, v40, v41 offset0:32 offset1:48

.LBB0_1242:
	v_readfirstlane_b32 s2, v122
	v_readfirstlane_b32 s3, v123
	s_add_i32 s3, s3, s2
	s_mov_b32 m0, s3
	s_add_i32 s2, s2, 0x3000
	s_cmp_eq_u32 s2, 0x1e800
	s_cselect_b32 s2, 0x20200, s2
	s_cmp_eq_u32 s2, 0x23200
	s_cselect_b32 s2, 0x12800, s2
	v_mov_b32_e32 v122, s2
	global_load_lds_dwordx4 v[96:97], off
	global_load_dwordx2 v[82:83], v[98:99], off
	s_add_i32 m0, s3, 0x1000
	s_nop 0
	global_load_lds_dwordx4 v[100:101], off
	s_add_i32 m0, s3, 0x2000
	s_nop 0
	global_load_lds_dwordx4 v[102:103], off
	global_load_dwordx2 v[84:85], v[104:105], off
	global_load_dwordx2 v[86:87], v[106:107], off
	v_lshl_add_u64 v[96:97], v[112:113], 0, v[96:97]
	v_lshl_add_u64 v[98:99], v[114:115], 0, v[98:99]
	v_lshl_add_u64 v[100:101], v[114:115], 0, v[100:101]
	v_lshl_add_u64 v[102:103], v[112:113], 0, v[102:103]
	v_lshl_add_u64 v[104:105], v[116:117], 0, v[104:105]
	v_lshl_add_u64 v[106:107], v[116:117], 0, v[106:107]
	v_readlane_b32 s73, v250, 16
	s_mov_b64 s[76:77], s[40:41]
